# v35 with the prompt-attention fast-loop head aligned to 64 bytes (code placement test)
# speedup vs baseline: 1.0105x; 1.0105x over previous
.Lqf_450:
	s_mov_b32 s44, s69
	s_mov_b32 s45, s68
	s_and_b64 vcc, exec, s[20:21]
	s_cbranch_vccnz .LBB0_465
	.p2alignl 6, 3212836864
